# deferred barrier wait plus write-through (sc1) on the 16-byte conversion stores of phases 6 and 14 so the XCD leader's write-back does not chase the early starters' dirty lines
# speedup vs baseline: 1.0126x; 1.0021x over previous
.LBB0_705:
	s_barrier
	s_waitcnt vmcnt(8)
	ds_write2_b32 v74, v2, v3 offset1:1
	ds_write2_b32 v74, v4, v5 offset0:2 offset1:3
	s_nop 0
	ds_write2_b32 v74, v6, v7 offset0:4 offset1:5
	ds_write2_b32 v74, v8, v9 offset0:6 offset1:7
	v_add_u32_e32 v2, 0x4100, v74
	s_nop 0
	ds_write2_b32 v2, v10, v11 offset1:1
	v_add_u32_e32 v2, 0x4108, v74
	ds_write2_b32 v2, v12, v13 offset1:1
	v_add_u32_e32 v2, 0x4110, v74
	s_nop 0
	ds_write2_b32 v2, v14, v15 offset1:1
	v_add_u32_e32 v2, 0x4118, v74
	ds_write2_b32 v2, v16, v17 offset1:1
	v_add_u32_e32 v2, 0x8200, v74
	s_nop 0
	ds_write2_b32 v2, v18, v19 offset1:1
	v_add_u32_e32 v2, 0x8208, v74
	ds_write2_b32 v2, v20, v21 offset1:1
	v_add_u32_e32 v2, 0x8210, v74
	s_nop 0
	ds_write2_b32 v2, v22, v23 offset1:1
	v_add_u32_e32 v2, 0x8218, v74
	ds_write2_b32 v2, v24, v25 offset1:1
	v_add_u32_e32 v2, 0xc300, v74
	s_nop 0
	ds_write2_b32 v2, v26, v27 offset1:1
	v_add_u32_e32 v2, 0xc308, v74
	ds_write2_b32 v2, v28, v29 offset1:1
	v_add_u32_e32 v2, 0xc310, v74
	s_nop 0
	ds_write2_b32 v2, v30, v31 offset1:1
	v_add_u32_e32 v2, 0xc318, v74
	ds_write2_b32 v2, v32, v33 offset1:1
	s_waitcnt lgkmcnt(0)
	s_barrier
	ds_read2_b32 v[2:3], v75 offset1:65
	ds_read2_b32 v[4:5], v75 offset0:130 offset1:195
	v_add_u32_e32 v8, 0x400, v75
	ds_read2_b32 v[6:7], v8 offset0:4 offset1:69
	ds_read2_b32 v[8:9], v8 offset0:134 offset1:199
	v_add_u32_e32 v10, 0x4400, v75
	s_waitcnt lgkmcnt(3)
	v_cvt_pk_bf16_f32 v2, v2, v3
	s_waitcnt lgkmcnt(2)
	v_cvt_pk_bf16_f32 v3, v4, v5
	s_waitcnt lgkmcnt(1)
	v_cvt_pk_bf16_f32 v4, v6, v7
	v_add_u32_e32 v6, 0x4000, v75
	v_add_u32_e32 v12, 0x4600, v75
	s_waitcnt lgkmcnt(0)
	v_cvt_pk_bf16_f32 v5, v8, v9
	ds_read2_b32 v[6:7], v6 offset0:64 offset1:129
	v_add_u32_e32 v8, 0x4200, v75
	ds_read2_b32 v[10:11], v10 offset0:68 offset1:133
	ds_read2_b32 v[12:13], v12 offset0:70 offset1:135
	ds_read2_b32 v[8:9], v8 offset0:66 offset1:131
	s_waitcnt vmcnt(0)
	global_store_dwordx4 v[70:71], v[2:5], off sc1
	s_cmpk_lt_i32 s25, 0x13d0
	s_mov_b32 s12, s25
	s_waitcnt lgkmcnt(3)
	v_cvt_pk_bf16_f32 v2, v6, v7
	s_waitcnt lgkmcnt(2)
	v_cvt_pk_bf16_f32 v4, v10, v11
	s_waitcnt lgkmcnt(1)
	v_cvt_pk_bf16_f32 v5, v12, v13
	v_add_u32_e32 v6, 0x8000, v75
	v_add_u32_e32 v10, 0x8400, v75
	v_add_u32_e32 v12, 0x8800, v75
	s_waitcnt lgkmcnt(0)
	v_cvt_pk_bf16_f32 v3, v8, v9
	ds_read2_b32 v[6:7], v6 offset0:128 offset1:193
	ds_read2_b32 v[8:9], v10 offset0:2 offset1:67
	ds_read2_b32 v[10:11], v10 offset0:132 offset1:197
	ds_read2_b32 v[12:13], v12 offset0:6 offset1:71
	global_store_dwordx4 v[70:71], v[2:5], off offset:128 sc1
	v_mov_b32_e32 v14, v42
	v_mov_b32_e32 v15, v43
	s_waitcnt lgkmcnt(3)
	v_cvt_pk_bf16_f32 v2, v6, v7
	s_waitcnt lgkmcnt(2)
	v_cvt_pk_bf16_f32 v3, v8, v9
	s_waitcnt lgkmcnt(1)
	v_cvt_pk_bf16_f32 v4, v10, v11
	s_waitcnt lgkmcnt(0)
	v_cvt_pk_bf16_f32 v5, v12, v13
	v_add_u32_e32 v6, 0xc200, v75
	v_add_u32_e32 v8, 0xc400, v75
	v_add_u32_e32 v10, 0xc600, v75
	v_add_u32_e32 v12, 0xc800, v75
	ds_read2_b32 v[6:7], v6 offset0:64 offset1:129
	ds_read2_b32 v[8:9], v8 offset0:66 offset1:131
	ds_read2_b32 v[10:11], v10 offset0:68 offset1:133
	ds_read2_b32 v[12:13], v12 offset0:70 offset1:135
	global_store_dwordx4 v[70:71], v[2:5], off offset:256 sc1
	v_mov_b32_e32 v16, v44
	v_mov_b32_e32 v17, v45
	s_waitcnt lgkmcnt(3)
	v_cvt_pk_bf16_f32 v2, v6, v7
	s_waitcnt lgkmcnt(2)
	v_cvt_pk_bf16_f32 v3, v8, v9
	s_waitcnt lgkmcnt(1)
	v_cvt_pk_bf16_f32 v4, v10, v11
	s_waitcnt lgkmcnt(0)
	v_cvt_pk_bf16_f32 v5, v12, v13
	global_store_dwordx4 v[70:71], v[2:5], off offset:384 sc1
	v_mov_b64_e32 v[70:71], v[72:73]
	v_mov_b32_e32 v6, v34
	v_mov_b32_e32 v2, v38
	v_mov_b32_e32 v3, v39
	v_mov_b32_e32 v4, v40
	v_mov_b32_e32 v5, v41
	v_mov_b32_e32 v7, v35
	v_mov_b32_e32 v8, v36
	v_mov_b32_e32 v9, v37
	v_mov_b32_e32 v10, v46
	v_mov_b32_e32 v11, v47
	v_mov_b32_e32 v12, v48
	v_mov_b32_e32 v13, v49
	v_mov_b32_e32 v18, v54
	v_mov_b32_e32 v19, v55
	v_mov_b32_e32 v20, v56
	v_mov_b32_e32 v21, v57
	v_mov_b32_e32 v22, v50
	v_mov_b32_e32 v23, v51
	v_mov_b32_e32 v24, v52
	v_mov_b32_e32 v25, v53
	v_mov_b32_e32 v26, v62
	v_mov_b32_e32 v27, v63
	v_mov_b32_e32 v28, v64
	v_mov_b32_e32 v29, v65
	v_mov_b32_e32 v30, v58
	v_mov_b32_e32 v31, v59
	v_mov_b32_e32 v32, v60
	v_mov_b32_e32 v33, v61
	s_cbranch_scc0 .LBB0_728

.LBB0_1302:
	s_barrier
	s_waitcnt vmcnt(8)
	ds_write2_b32 v74, v2, v3 offset1:1
	ds_write2_b32 v74, v4, v5 offset0:2 offset1:3
	s_nop 0
	ds_write2_b32 v74, v6, v7 offset0:4 offset1:5
	ds_write2_b32 v74, v8, v9 offset0:6 offset1:7
	v_add_u32_e32 v2, 0x4100, v74
	s_nop 0
	ds_write2_b32 v2, v10, v11 offset1:1
	v_add_u32_e32 v2, 0x4108, v74
	ds_write2_b32 v2, v12, v13 offset1:1
	v_add_u32_e32 v2, 0x4110, v74
	s_nop 0
	ds_write2_b32 v2, v14, v15 offset1:1
	v_add_u32_e32 v2, 0x4118, v74
	ds_write2_b32 v2, v16, v17 offset1:1
	v_add_u32_e32 v2, 0x8200, v74
	s_nop 0
	ds_write2_b32 v2, v18, v19 offset1:1
	v_add_u32_e32 v2, 0x8208, v74
	ds_write2_b32 v2, v20, v21 offset1:1
	v_add_u32_e32 v2, 0x8210, v74
	s_nop 0
	ds_write2_b32 v2, v22, v23 offset1:1
	v_add_u32_e32 v2, 0x8218, v74
	ds_write2_b32 v2, v24, v25 offset1:1
	v_add_u32_e32 v2, 0xc300, v74
	s_nop 0
	ds_write2_b32 v2, v26, v27 offset1:1
	v_add_u32_e32 v2, 0xc308, v74
	ds_write2_b32 v2, v28, v29 offset1:1
	v_add_u32_e32 v2, 0xc310, v74
	s_nop 0
	ds_write2_b32 v2, v30, v31 offset1:1
	v_add_u32_e32 v2, 0xc318, v74
	ds_write2_b32 v2, v32, v33 offset1:1
	s_waitcnt lgkmcnt(0)
	s_barrier
	ds_read2_b32 v[2:3], v75 offset1:65
	ds_read2_b32 v[4:5], v75 offset0:130 offset1:195
	v_add_u32_e32 v8, 0x400, v75
	ds_read2_b32 v[6:7], v8 offset0:4 offset1:69
	ds_read2_b32 v[8:9], v8 offset0:134 offset1:199
	v_add_u32_e32 v10, 0x4400, v75
	s_waitcnt lgkmcnt(3)
	v_cvt_pk_bf16_f32 v2, v2, v3
	s_waitcnt lgkmcnt(2)
	v_cvt_pk_bf16_f32 v3, v4, v5
	s_waitcnt lgkmcnt(1)
	v_cvt_pk_bf16_f32 v4, v6, v7
	v_add_u32_e32 v6, 0x4000, v75
	v_add_u32_e32 v12, 0x4600, v75
	s_waitcnt lgkmcnt(0)
	v_cvt_pk_bf16_f32 v5, v8, v9
	ds_read2_b32 v[6:7], v6 offset0:64 offset1:129
	v_add_u32_e32 v8, 0x4200, v75
	ds_read2_b32 v[10:11], v10 offset0:68 offset1:133
	ds_read2_b32 v[12:13], v12 offset0:70 offset1:135
	ds_read2_b32 v[8:9], v8 offset0:66 offset1:131
	s_waitcnt vmcnt(0)
	global_store_dwordx4 v[70:71], v[2:5], off sc1
	s_cmpk_lt_i32 s23, 0x19d0
	s_mov_b32 s10, s23
	s_waitcnt lgkmcnt(3)
	v_cvt_pk_bf16_f32 v2, v6, v7
	s_waitcnt lgkmcnt(2)
	v_cvt_pk_bf16_f32 v4, v10, v11
	s_waitcnt lgkmcnt(1)
	v_cvt_pk_bf16_f32 v5, v12, v13
	v_add_u32_e32 v6, 0x8000, v75
	v_add_u32_e32 v10, 0x8400, v75
	v_add_u32_e32 v12, 0x8800, v75
	s_waitcnt lgkmcnt(0)
	v_cvt_pk_bf16_f32 v3, v8, v9
	ds_read2_b32 v[6:7], v6 offset0:128 offset1:193
	ds_read2_b32 v[8:9], v10 offset0:2 offset1:67
	ds_read2_b32 v[10:11], v10 offset0:132 offset1:197
	ds_read2_b32 v[12:13], v12 offset0:6 offset1:71
	global_store_dwordx4 v[70:71], v[2:5], off offset:128 sc1
	v_mov_b32_e32 v14, v42
	v_mov_b32_e32 v15, v43
	s_waitcnt lgkmcnt(3)
	v_cvt_pk_bf16_f32 v2, v6, v7
	s_waitcnt lgkmcnt(2)
	v_cvt_pk_bf16_f32 v3, v8, v9
	s_waitcnt lgkmcnt(1)
	v_cvt_pk_bf16_f32 v4, v10, v11
	s_waitcnt lgkmcnt(0)
	v_cvt_pk_bf16_f32 v5, v12, v13
	v_add_u32_e32 v6, 0xc200, v75
	v_add_u32_e32 v8, 0xc400, v75
	v_add_u32_e32 v10, 0xc600, v75
	v_add_u32_e32 v12, 0xc800, v75
	ds_read2_b32 v[6:7], v6 offset0:64 offset1:129
	ds_read2_b32 v[8:9], v8 offset0:66 offset1:131
	ds_read2_b32 v[10:11], v10 offset0:68 offset1:133
	ds_read2_b32 v[12:13], v12 offset0:70 offset1:135
	global_store_dwordx4 v[70:71], v[2:5], off offset:256 sc1
	v_mov_b32_e32 v16, v44
	v_mov_b32_e32 v17, v45
	s_waitcnt lgkmcnt(3)
	v_cvt_pk_bf16_f32 v2, v6, v7
	s_waitcnt lgkmcnt(2)
	v_cvt_pk_bf16_f32 v3, v8, v9
	s_waitcnt lgkmcnt(1)
	v_cvt_pk_bf16_f32 v4, v10, v11
	s_waitcnt lgkmcnt(0)
	v_cvt_pk_bf16_f32 v5, v12, v13
	global_store_dwordx4 v[70:71], v[2:5], off offset:384 sc1
	v_mov_b64_e32 v[70:71], v[72:73]
	v_mov_b32_e32 v6, v34
	v_mov_b32_e32 v2, v38
	v_mov_b32_e32 v3, v39
	v_mov_b32_e32 v4, v40
	v_mov_b32_e32 v5, v41
	v_mov_b32_e32 v7, v35
	v_mov_b32_e32 v8, v36
	v_mov_b32_e32 v9, v37
	v_mov_b32_e32 v10, v46
	v_mov_b32_e32 v11, v47
	v_mov_b32_e32 v12, v48
	v_mov_b32_e32 v13, v49
	v_mov_b32_e32 v18, v54
	v_mov_b32_e32 v19, v55
	v_mov_b32_e32 v20, v56
	v_mov_b32_e32 v21, v57
	v_mov_b32_e32 v22, v50
	v_mov_b32_e32 v23, v51
	v_mov_b32_e32 v24, v52
	v_mov_b32_e32 v25, v53
	v_mov_b32_e32 v26, v62
	v_mov_b32_e32 v27, v63
	v_mov_b32_e32 v28, v64
	v_mov_b32_e32 v29, v65
	v_mov_b32_e32 v30, v58
	v_mov_b32_e32 v31, v59
	v_mov_b32_e32 v32, v60
	v_mov_b32_e32 v33, v61
	s_cbranch_scc0 .LBB0_1325
